# mixb GLA scan loop: q_e/P/decay loads of each step issued one step ahead into spare VGPRs (single vmcnt at step top), removes in-order vmcnt stalls
# speedup vs baseline: 1.0294x; 1.0025x over previous
.LBB0_421:
	s_cmp_lt_i32 s56, -3
	s_cbranch_scc1 .LBB0_430
	s_cmp_eq_u32 s27, 0
	s_cselect_b64 s[24:25], -1, 0
	s_lshr_b32 s20, s26, 6
	s_lshl_b32 s29, s28, 8
	s_lshl_b32 s26, s28, 1
	s_and_b64 s[6:7], s[24:25], exec
	s_cselect_b32 s6, s54, 0x18d24000
	s_add_u32 s59, s42, s6
	s_addc_u32 s60, s43, 0
	s_and_b64 s[6:7], s[24:25], exec
	s_cselect_b32 s6, 0, s57
	s_add_i32 s6, s20, s6
	s_mov_b32 s7, s9
	s_lshl_b64 s[30:31], s[6:7], 10
	s_or_b32 s30, s30, s29
	s_or_b64 s[30:31], s[30:31], s[8:9]
	s_lshl_b64 s[30:31], s[30:31], 7
	s_lshl_b32 s6, s6, 3
	s_or_b32 s26, s26, s27
	v_lshl_add_u64 v[34:35], v[136:137], 0, s[30:31]
	v_mov_b32_e32 v159, v111
	s_or_b32 s6, s26, s6
	v_lshl_add_u64 v[36:37], v[34:35], 0, v[110:111]
	v_lshl_add_u64 v[34:35], v[34:35], 0, v[158:159]
	s_lshl_b64 s[6:7], s[6:7], 14
	global_load_dwordx4 v[58:61], v[36:37], off
	global_load_dwordx4 v[62:65], v[34:35], off
	v_lshl_add_u64 v[34:35], v[138:139], 0, s[6:7]
	v_mov_b32_e32 v161, v111
	v_lshl_add_u64 v[36:37], v[34:35], 0, v[160:161]
	v_mov_b32_e32 v163, v111
	s_waitcnt vmcnt(6)
	v_lshl_add_u64 v[38:39], v[34:35], 0, v[162:163]
	global_load_dwordx4 v[78:81], v[36:37], off
	global_load_dwordx4 v[74:77], v[38:39], off
	v_lshl_add_u64 v[36:37], v[34:35], 0, v[110:111]
	v_lshl_add_u64 v[34:35], v[34:35], 0, v[158:159]
	global_load_dwordx4 v[70:73], v[36:37], off
	global_load_dwordx4 v[66:69], v[34:35], off
	s_lshl_b32 s6, s28, 9
	s_add_u32 s6, s59, s6
	s_addc_u32 s7, s60, 0
	s_lshl_b32 s28, s8, 1
	s_add_u32 s6, s6, s28
	s_addc_u32 s7, s7, 0
	v_lshlrev_b32_e32 v34, 1, v116
	v_mov_b32_e32 v35, v111
	v_lshl_add_u64 v[166:167], s[6:7], 0, v[34:35]
	s_or_b32 s6, s8, s29
	s_mov_b32 s58, 0
	s_mov_b32 s27, s9
	s_add_i32 s59, s56, 3
	s_add_i32 s60, s56, 4
	s_lshl_b32 s61, s6, 7
	s_mov_b32 s62, s57
	s_and_b64 s[98:99], s[24:25], exec
	s_cselect_b32 s98, 0, s62
	s_add_i32 s98, s98, s20
	s_ashr_i32 s99, s98, 31
	s_lshl_b64 s[98:99], s[98:99], 3
	s_or_b64 s[98:99], s[98:99], s[26:27]
	s_lshl_b64 s[100:101], s[98:99], 9
	v_lshl_add_u64 v[82:83], v[144:145], 0, s[100:101]
	global_load_dword v250, v[82:83], off
	global_load_dword v251, v[82:83], off offset:64
	global_load_dword v252, v[82:83], off offset:128
	global_load_dword v253, v[82:83], off offset:192
	global_load_dword v254, v[82:83], off offset:256
	global_load_dword v186, v[82:83], off offset:320
	global_load_dword v151, v[82:83], off offset:384
	global_load_dword v153, v[82:83], off offset:448
	s_cmp_gt_i32 s56, 0
	s_cbranch_scc1 .Lscpf_l0_pre
	s_lshl_b64 s[100:101], s[98:99], 14
	v_lshl_add_u64 v[236:237], v[140:141], 0, s[100:101]
	global_load_dwordx4 v[224:227], v[236:237], off
	global_load_dwordx4 v[228:231], v[236:237], off offset:64
	global_load_dwordx4 v[232:235], v[236:237], off offset:128
	s_nop 0
	global_load_dwordx4 v[236:239], v[236:237], off offset:192
	s_lshl_b64 s[100:101], s[98:99], 13
	v_lshl_add_u64 v[244:245], v[142:143], 0, s[100:101]
	global_load_dwordx4 v[240:243], v[244:245], off
	s_nop 0
	global_load_dwordx4 v[244:247], v[244:245], off offset:64

.LBB0_423:
	s_nop 3
	ds_read_b128 v[196:199], v188 offset:17408
	ds_read_b128 v[200:203], v188 offset:17472
	v_pk_mul_f32 v[4:5], v[4:5], v[182:183] op_sel_hi:[1,0]
	v_pk_mul_f32 v[2:3], v[2:3], v[182:183] op_sel_hi:[1,0]
	v_pk_mul_f32 v[8:9], v[8:9], v[180:181] op_sel_hi:[1,0]
	v_pk_mul_f32 v[6:7], v[6:7], v[180:181] op_sel_hi:[1,0]
	s_waitcnt lgkmcnt(1)
	v_mfma_f32_16x16x32_bf16 v[2:5], v[86:89], v[196:199], v[2:5]
	ds_read_b128 v[196:199], v125 offset:17408
	v_pk_mul_f32 v[20:21], v[20:21], v[178:179] op_sel_hi:[1,0]
	v_pk_mul_f32 v[18:19], v[18:19], v[178:179] op_sel_hi:[1,0]
	s_waitcnt lgkmcnt(1)
	v_mfma_f32_16x16x32_bf16 v[2:5], v[82:85], v[200:203], v[2:5]
	ds_read_b128 v[200:203], v125 offset:17472
	v_pk_mul_f32 v[12:13], v[12:13], v[176:177] op_sel_hi:[1,0]
	v_pk_mul_f32 v[10:11], v[10:11], v[176:177] op_sel_hi:[1,0]
	s_waitcnt lgkmcnt(1)
	v_mfma_f32_16x16x32_bf16 v[6:9], v[86:89], v[196:199], v[6:9]
	ds_read_b128 v[196:199], v189 offset:17408
	v_pk_mul_f32 v[24:25], v[24:25], v[174:175] op_sel_hi:[1,0]
	v_pk_mul_f32 v[22:23], v[22:23], v[174:175] op_sel_hi:[1,0]
	s_waitcnt lgkmcnt(1)
	v_mfma_f32_16x16x32_bf16 v[6:9], v[82:85], v[200:203], v[6:9]
	ds_read_b128 v[200:203], v189 offset:17472
	ds_read_b128 v[174:177], v127 offset:17472
	v_pk_mul_f32 v[16:17], v[16:17], v[172:173] op_sel_hi:[1,0]
	s_waitcnt lgkmcnt(2)
	v_mfma_f32_16x16x32_bf16 v[18:21], v[86:89], v[196:199], v[18:21]
	ds_read_b128 v[196:199], v190 offset:17408
	v_pk_mul_f32 v[14:15], v[14:15], v[172:173] op_sel_hi:[1,0]
	v_pk_mul_f32 v[28:29], v[28:29], v[170:171] op_sel_hi:[1,0]
	s_waitcnt lgkmcnt(2)
	v_mfma_f32_16x16x32_bf16 v[18:21], v[82:85], v[200:203], v[18:21]
	ds_read_b128 v[200:203], v190 offset:17472
	v_pk_mul_f32 v[26:27], v[26:27], v[170:171] op_sel_hi:[1,0]
	v_pk_mul_f32 v[32:33], v[32:33], v[168:169] op_sel_hi:[1,0]
	s_waitcnt lgkmcnt(1)
	v_mfma_f32_16x16x32_bf16 v[10:13], v[86:89], v[196:199], v[10:13]
	ds_read_b128 v[196:199], v127 offset:17408
	v_pk_mul_f32 v[30:31], v[30:31], v[168:169] op_sel_hi:[1,0]
	s_add_i32 s62, s62, -1
	s_waitcnt lgkmcnt(0)
	v_mfma_f32_16x16x32_bf16 v[22:25], v[86:89], v[196:199], v[22:25]
	ds_read_b128 v[196:199], v129 offset:17408
	s_cmp_eq_u32 s60, s58
	v_mfma_f32_16x16x32_bf16 v[22:25], v[82:85], v[174:177], v[22:25]
	ds_read_b128 v[172:175], v129 offset:17472
	s_waitcnt lgkmcnt(1)
	v_mfma_f32_16x16x32_bf16 v[14:17], v[86:89], v[196:199], v[14:17]
	ds_read_b128 v[196:199], v131 offset:17408
	s_waitcnt lgkmcnt(1)
	v_mfma_f32_16x16x32_bf16 v[14:17], v[82:85], v[172:175], v[14:17]
	ds_read_b128 v[170:173], v131 offset:17472
	ds_read_b128 v[174:177], v187 offset:17408
	s_waitcnt lgkmcnt(2)
	v_mfma_f32_16x16x32_bf16 v[26:29], v[86:89], v[196:199], v[26:29]
	s_waitcnt lgkmcnt(1)
	v_mfma_f32_16x16x32_bf16 v[26:29], v[82:85], v[170:173], v[26:29]
	ds_read_b128 v[168:171], v187 offset:17472
	s_waitcnt lgkmcnt(1)
	v_mfma_f32_16x16x32_bf16 v[30:33], v[86:89], v[174:177], v[30:33]
	v_mfma_f32_16x16x32_bf16 v[10:13], v[82:85], v[200:203], v[10:13]
	s_waitcnt lgkmcnt(0)
	v_mfma_f32_16x16x32_bf16 v[30:33], v[82:85], v[168:171], v[30:33]
	s_cbranch_scc1 .LBB0_430
.LBB0_424:
	s_cmp_ge_i32 s58, s56
	s_cselect_b64 s[30:31], -1, 0
	s_and_b64 s[6:7], s[24:25], exec
	s_cselect_b32 s6, s58, s62
	s_add_i32 s28, s6, s20
	s_ashr_i32 s29, s28, 31
	s_cmp_gt_i32 s58, s56
	s_cbranch_scc1 .Lscpf_l0_w4
	s_waitcnt vmcnt(0)
	s_branch .Lscpf_l0_wd
.Lscpf_l0_w4:
	s_waitcnt vmcnt(4)
.Lscpf_l0_wd:
	v_mov_b32_e32 v182, v250
	v_mov_b32_e32 v180, v251
	v_mov_b32_e32 v178, v252
	v_mov_b32_e32 v176, v253
	v_mov_b32_e32 v174, v254
	v_mov_b32_e32 v172, v186
	v_mov_b32_e32 v170, v151
	v_mov_b32_e32 v168, v153
	s_cmp_lt_i32 s58, s56
	s_cbranch_scc1 .Lscpf_l0_nq
	v_mov_b32_e32 v38, v224
	v_mov_b32_e32 v39, v225
	v_mov_b32_e32 v40, v226
	v_mov_b32_e32 v41, v227
	v_mov_b32_e32 v34, v228
	v_mov_b32_e32 v35, v229
	v_mov_b32_e32 v36, v230
	v_mov_b32_e32 v37, v231
	v_mov_b32_e32 v42, v232
	v_mov_b32_e32 v43, v233
	v_mov_b32_e32 v44, v234
	v_mov_b32_e32 v45, v235
	v_mov_b32_e32 v46, v236
	v_mov_b32_e32 v47, v237
	v_mov_b32_e32 v48, v238
	v_mov_b32_e32 v49, v239
	v_mov_b32_e32 v54, v240
	v_mov_b32_e32 v55, v241
	v_mov_b32_e32 v56, v242
	v_mov_b32_e32 v57, v243
	v_mov_b32_e32 v50, v244
	v_mov_b32_e32 v51, v245
	v_mov_b32_e32 v52, v246
	v_mov_b32_e32 v53, v247
.Lscpf_l0_nq:
	s_barrier
	ds_write_b128 v191, v[66:69] offset:17408
	ds_write_b128 v191, v[70:73] offset:22016
	ds_write_b128 v191, v[74:77] offset:26624
	ds_write_b128 v191, v[78:81] offset:31232
	ds_write_b128 v191, v[62:65] offset:35840
	v_cndmask_b32_e64 v62, 0, 1, s[30:31]
	v_cmp_ne_u32_e64 s[6:7], 1, v62
	s_andn2_b64 vcc, exec, s[30:31]
	ds_write_b128 v191, v[58:61] offset:40448
	s_cbranch_vccnz .LBB0_428
	v_cvt_pk_bf16_f32 v58, v2, s0
	ds_write_b16 v192, v58
	v_cvt_pk_bf16_f32 v58, v3, s0
	ds_write_b16 v192, v58 offset:272
	v_cvt_pk_bf16_f32 v58, v4, s0
	ds_write_b16 v192, v58 offset:544
	v_cvt_pk_bf16_f32 v58, v5, s0
	ds_write_b16 v192, v58 offset:816
	v_cvt_pk_bf16_f32 v58, v6, s0
	ds_write_b16 v192, v58 offset:32
	v_cvt_pk_bf16_f32 v58, v7, s0
	ds_write_b16 v192, v58 offset:304
	v_cvt_pk_bf16_f32 v58, v8, s0
	ds_write_b16 v192, v58 offset:576
	v_cvt_pk_bf16_f32 v58, v9, s0
	ds_write_b16 v192, v58 offset:848
	v_cvt_pk_bf16_f32 v58, v18, s0
	ds_write_b16 v192, v58 offset:64
	v_cvt_pk_bf16_f32 v58, v19, s0
	ds_write_b16 v192, v58 offset:336
	v_cvt_pk_bf16_f32 v58, v20, s0
	ds_write_b16 v192, v58 offset:608
	v_cvt_pk_bf16_f32 v58, v21, s0
	ds_write_b16 v192, v58 offset:880
	v_cvt_pk_bf16_f32 v58, v10, s0
	ds_write_b16 v192, v58 offset:96
	v_cvt_pk_bf16_f32 v58, v11, s0
	ds_write_b16 v192, v58 offset:368
	v_cvt_pk_bf16_f32 v58, v12, s0
	ds_write_b16 v192, v58 offset:640
	v_cvt_pk_bf16_f32 v58, v13, s0
	ds_write_b16 v192, v58 offset:912
	v_cvt_pk_bf16_f32 v58, v22, s0
	ds_write_b16 v192, v58 offset:128
	v_cvt_pk_bf16_f32 v58, v23, s0
	ds_write_b16 v192, v58 offset:400
	v_cvt_pk_bf16_f32 v58, v24, s0
	ds_write_b16 v192, v58 offset:672
	v_cvt_pk_bf16_f32 v58, v25, s0
	ds_write_b16 v192, v58 offset:944
	v_cvt_pk_bf16_f32 v58, v14, s0
	ds_write_b16 v192, v58 offset:160
	v_cvt_pk_bf16_f32 v58, v15, s0
	ds_write_b16 v192, v58 offset:432
	v_cvt_pk_bf16_f32 v58, v16, s0
	ds_write_b16 v192, v58 offset:704
	v_cvt_pk_bf16_f32 v58, v17, s0
	ds_write_b16 v192, v58 offset:976
	v_cvt_pk_bf16_f32 v58, v26, s0
	ds_write_b16 v192, v58 offset:192
	v_cvt_pk_bf16_f32 v58, v27, s0
	ds_write_b16 v192, v58 offset:464
	v_cvt_pk_bf16_f32 v58, v28, s0
	ds_write_b16 v192, v58 offset:736
	v_cvt_pk_bf16_f32 v58, v29, s0
	ds_write_b16 v192, v58 offset:1008
	v_cvt_pk_bf16_f32 v58, v30, s0
	ds_write_b16 v192, v58 offset:224
	v_cvt_pk_bf16_f32 v58, v31, s0
	ds_write_b16 v192, v58 offset:496
	v_cvt_pk_bf16_f32 v58, v32, s0
	ds_write_b16 v192, v58 offset:768
	v_cvt_pk_bf16_f32 v58, v33, s0
	ds_write_b16 v192, v58 offset:1040
.LBB0_428:
	s_add_i32 s58, s58, 1
	s_min_i32 s29, s58, s59
	s_sub_i32 s63, s57, s29
	s_and_b64 s[30:31], s[24:25], exec
	s_cselect_b32 s29, s29, s63
	s_add_i32 s30, s29, s20
	s_ashr_i32 s31, s30, 31
	s_lshl_b64 s[98:99], s[30:31], 3
	s_or_b64 s[98:99], s[98:99], s[26:27]
	s_lshl_b32 s29, s26, 14
	s_lshl_b64 s[30:31], s[30:31], 17
	s_or_b32 s64, s30, s29
	s_mov_b32 s65, s31
	v_lshl_add_u64 v[58:59], v[146:147], 0, s[64:65]
	v_add_co_u32_e32 v60, vcc, s33, v58
	s_waitcnt lgkmcnt(0)
	s_nop 0
	v_addc_co_u32_e32 v61, vcc, 0, v59, vcc
	s_barrier
	global_load_dwordx4 v[66:69], v[58:59], off
	global_load_dwordx4 v[70:73], v[60:61], off
	v_add_co_u32_e32 v60, vcc, 0x2000, v58
	s_or_b32 s30, s30, s61
	s_nop 0
	v_addc_co_u32_e32 v61, vcc, 0, v59, vcc
	v_add_co_u32_e32 v58, vcc, 0x3000, v58
	s_nop 1
	v_addc_co_u32_e32 v59, vcc, 0, v59, vcc
	global_load_dwordx4 v[74:77], v[60:61], off
	global_load_dwordx4 v[78:81], v[58:59], off
	v_lshl_add_u64 v[58:59], v[148:149], 0, s[30:31]
	v_add_co_u32_e32 v60, vcc, 0x1000, v58
	s_nop 1
	v_addc_co_u32_e32 v61, vcc, 0, v59, vcc
	global_load_dwordx4 v[62:65], v[58:59], off
	s_nop 0
	global_load_dwordx4 v[58:61], v[60:61], off
	s_cmp_gt_i32 s58, s59
	s_cbranch_scc1 .Lscpf_l0_nopf
	s_lshl_b64 s[100:101], s[98:99], 9
	v_lshl_add_u64 v[82:83], v[144:145], 0, s[100:101]
	global_load_dword v250, v[82:83], off
	global_load_dword v251, v[82:83], off offset:64
	global_load_dword v252, v[82:83], off offset:128
	global_load_dword v253, v[82:83], off offset:192
	global_load_dword v254, v[82:83], off offset:256
	global_load_dword v186, v[82:83], off offset:320
	global_load_dword v151, v[82:83], off offset:384
	global_load_dword v153, v[82:83], off offset:448
	s_cmp_lt_i32 s58, s56
	s_cbranch_scc1 .Lscpf_l0_nopf
	s_lshl_b64 s[100:101], s[98:99], 14
	v_lshl_add_u64 v[236:237], v[140:141], 0, s[100:101]
	global_load_dwordx4 v[224:227], v[236:237], off
	global_load_dwordx4 v[228:231], v[236:237], off offset:64
	global_load_dwordx4 v[232:235], v[236:237], off offset:128
	s_nop 0
	global_load_dwordx4 v[236:239], v[236:237], off offset:192
	s_lshl_b64 s[100:101], s[98:99], 13
	v_lshl_add_u64 v[244:245], v[142:143], 0, s[100:101]
	global_load_dwordx4 v[240:243], v[244:245], off
	s_nop 0
	global_load_dwordx4 v[244:247], v[244:245], off offset:64
.Lscpf_l0_nopf:
	ds_read_b128 v[86:89], v123 offset:35840
	ds_read_b128 v[82:85], v123 offset:35904
	s_and_b64 vcc, exec, s[6:7]
	s_cbranch_vccnz .LBB0_423
	v_add_u32_e32 v91, v121, v117
	ds_read_b128 v[196:199], v194 offset:35840
	ds_read_b128 v[200:203], v91 offset:35840
	ds_read_b128 v[204:207], v194 offset:35904
	ds_read_b128 v[208:211], v91 offset:35904
	ds_read_b128 v[212:215], v193
	s_waitcnt lgkmcnt(3)
	v_mfma_f32_16x16x32_bf16 v[200:203], v[200:203], v[54:57], 0
	v_lshl_add_u32 v184, s28, 6, v119
	v_ashrrev_i32_e32 v185, 31, v184
	v_lshlrev_b64 v[184:185], 11, v[184:185]
	s_waitcnt lgkmcnt(1)
	v_mfma_f32_16x16x32_bf16 v[200:203], v[208:211], v[50:53], v[200:203]
	ds_read_b128 v[208:211], v193 offset:64
	v_lshl_add_u64 v[184:185], v[166:167], 0, v[184:185]
	ds_read_b128 v[220:223], v193 offset:13120
	s_waitcnt lgkmcnt(2)
	v_mfma_f32_16x16x32_bf16 v[200:203], v[212:215], v[38:41], v[200:203]
	ds_read_b128 v[212:215], v193 offset:128
	ds_read_b128 v[216:219], v193 offset:13056
	s_waitcnt lgkmcnt(3)
	v_mfma_f32_16x16x32_bf16 v[200:203], v[208:211], v[34:37], v[200:203]
	ds_read_b128 v[208:211], v193 offset:192
	v_mfma_f32_16x16x32_bf16 v[196:199], v[196:199], v[54:57], 0
	s_waitcnt lgkmcnt(2)
	v_mfma_f32_16x16x32_bf16 v[200:203], v[212:215], v[42:45], v[200:203]
	ds_read_b128 v[212:215], v193 offset:8704
	v_mfma_f32_16x16x32_bf16 v[196:199], v[204:207], v[50:53], v[196:199]
	ds_read_b128 v[204:207], v193 offset:4416
	s_waitcnt lgkmcnt(2)
	v_mfma_f32_16x16x32_bf16 v[200:203], v[208:211], v[46:49], v[200:203]
	ds_read_b128 v[208:211], v193 offset:4352
	s_waitcnt lgkmcnt(0)
	v_mfma_f32_16x16x32_bf16 v[196:199], v[208:211], v[38:41], v[196:199]
	ds_read_b128 v[208:211], v193 offset:4480
	s_nop 3
	v_cvt_pk_bf16_f32 v200, v200, v201
	v_cvt_pk_bf16_f32 v201, v202, v203
	v_mfma_f32_16x16x32_bf16 v[196:199], v[204:207], v[34:37], v[196:199]
	ds_read_b128 v[204:207], v193 offset:4544
	global_store_dwordx2 v[184:185], v[200:201], off
	ds_read_b128 v[200:203], v193 offset:13248
	s_waitcnt lgkmcnt(2)
	v_mfma_f32_16x16x32_bf16 v[196:199], v[208:211], v[42:45], v[196:199]
	ds_read_b128 v[208:211], v194 offset:38144
	s_waitcnt lgkmcnt(2)
	v_mfma_f32_16x16x32_bf16 v[196:199], v[204:207], v[46:49], v[196:199]
	ds_read_b128 v[204:207], v194 offset:38208
	s_waitcnt lgkmcnt(1)
	v_mfma_f32_16x16x32_bf16 v[208:211], v[208:211], v[54:57], 0
	s_nop 4
	v_cvt_pk_bf16_f32 v196, v196, v197
	s_waitcnt lgkmcnt(0)
	v_mfma_f32_16x16x32_bf16 v[204:207], v[204:207], v[50:53], v[208:211]
	v_cvt_pk_bf16_f32 v197, v198, v199
	global_store_dwordx2 v[184:185], v[196:197], off offset:32
	s_nop 0
	ds_read_b128 v[208:211], v193 offset:8768
	v_mfma_f32_16x16x32_bf16 v[204:207], v[212:215], v[38:41], v[204:207]
	ds_read_b128 v[212:215], v193 offset:8832
	s_waitcnt lgkmcnt(1)
	v_mfma_f32_16x16x32_bf16 v[204:207], v[208:211], v[34:37], v[204:207]
	ds_read_b128 v[208:211], v193 offset:8896
	s_waitcnt lgkmcnt(1)
	v_mfma_f32_16x16x32_bf16 v[204:207], v[212:215], v[42:45], v[204:207]
	ds_read_b128 v[212:215], v194 offset:40448
	s_waitcnt lgkmcnt(1)
	v_mfma_f32_16x16x32_bf16 v[204:207], v[208:211], v[46:49], v[204:207]
	ds_read_b128 v[208:211], v194 offset:40512
	s_waitcnt lgkmcnt(1)
	v_mfma_f32_16x16x32_bf16 v[212:215], v[212:215], v[54:57], 0
	s_nop 4
	v_cvt_pk_bf16_f32 v204, v204, v205
	v_cvt_pk_bf16_f32 v205, v206, v207
	global_store_dwordx2 v[184:185], v[204:205], off offset:64
	s_waitcnt lgkmcnt(0)
	v_mfma_f32_16x16x32_bf16 v[208:211], v[208:211], v[50:53], v[212:215]
	s_nop 2
	ds_read_b128 v[212:215], v193 offset:13184
	v_mfma_f32_16x16x32_bf16 v[208:211], v[216:219], v[38:41], v[208:211]
	v_mfma_f32_16x16x32_bf16 v[208:211], v[220:223], v[34:37], v[208:211]
	s_waitcnt lgkmcnt(0)
	v_mfma_f32_16x16x32_bf16 v[196:199], v[212:215], v[42:45], v[208:211]
	v_mfma_f32_16x16x32_bf16 v[196:199], v[200:203], v[46:49], v[196:199]
	s_nop 7
	v_cvt_pk_bf16_f32 v196, v196, v197
	v_cvt_pk_bf16_f32 v197, v198, v199
	global_store_dwordx2 v[184:185], v[196:197], off offset:96
	s_branch .LBB0_423

.LBB0_1161:
	s_cmp_lt_i32 s54, -3
	s_cbranch_scc1 .LBB0_1170
	s_cmp_eq_u32 s27, 0
	s_cselect_b64 s[24:25], -1, 0
	s_lshr_b32 s20, s26, 6
	s_lshl_b32 s29, s28, 8
	s_lshl_b32 s26, s28, 1
	s_and_b64 s[6:7], s[24:25], exec
	s_cselect_b32 s6, s52, 0x18d24000
	s_add_u32 s57, s42, s6
	s_addc_u32 s58, s43, 0
	s_and_b64 s[6:7], s[24:25], exec
	s_cselect_b32 s6, 0, s55
	s_add_i32 s6, s20, s6
	s_mov_b32 s7, s9
	s_lshl_b64 s[30:31], s[6:7], 10
	s_or_b32 s30, s30, s29
	s_or_b64 s[30:31], s[30:31], s[8:9]
	s_lshl_b64 s[30:31], s[30:31], 7
	s_lshl_b32 s6, s6, 3
	s_or_b32 s26, s26, s27
	v_lshl_add_u64 v[34:35], v[138:139], 0, s[30:31]
	v_mov_b32_e32 v161, v111
	s_or_b32 s6, s26, s6
	v_lshl_add_u64 v[36:37], v[34:35], 0, v[110:111]
	v_lshl_add_u64 v[34:35], v[34:35], 0, v[160:161]
	s_lshl_b64 s[6:7], s[6:7], 14
	global_load_dwordx4 v[58:61], v[36:37], off
	global_load_dwordx4 v[62:65], v[34:35], off
	v_lshl_add_u64 v[34:35], v[140:141], 0, s[6:7]
	v_mov_b32_e32 v163, v111
	v_lshl_add_u64 v[36:37], v[34:35], 0, v[162:163]
	v_mov_b32_e32 v165, v111
	v_lshl_add_u64 v[38:39], v[34:35], 0, v[164:165]
	global_load_dwordx4 v[78:81], v[36:37], off
	global_load_dwordx4 v[74:77], v[38:39], off
	v_lshl_add_u64 v[36:37], v[34:35], 0, v[110:111]
	v_lshl_add_u64 v[34:35], v[34:35], 0, v[160:161]
	global_load_dwordx4 v[70:73], v[36:37], off
	global_load_dwordx4 v[66:69], v[34:35], off
	s_lshl_b32 s6, s28, 9
	s_add_u32 s6, s57, s6
	s_addc_u32 s7, s58, 0
	s_lshl_b32 s28, s8, 1
	s_add_u32 s6, s6, s28
	s_addc_u32 s7, s7, 0
	v_lshlrev_b32_e32 v34, 1, v116
	v_mov_b32_e32 v35, v111
	v_lshl_add_u64 v[168:169], s[6:7], 0, v[34:35]
	s_or_b32 s6, s8, s29
	s_mov_b32 s56, 0
	s_mov_b32 s27, s9
	s_add_i32 s57, s54, 3
	s_add_i32 s58, s54, 4
	s_lshl_b32 s59, s6, 7
	s_mov_b32 s60, s55
	s_and_b64 s[98:99], s[24:25], exec
	s_cselect_b32 s98, 0, s60
	s_add_i32 s98, s98, s20
	s_ashr_i32 s99, s98, 31
	s_lshl_b64 s[98:99], s[98:99], 3
	s_or_b64 s[98:99], s[98:99], s[26:27]
	s_lshl_b64 s[100:101], s[98:99], 9
	v_lshl_add_u64 v[82:83], v[146:147], 0, s[100:101]
	global_load_dword v246, v[82:83], off
	global_load_dword v247, v[82:83], off offset:64
	global_load_dword v248, v[82:83], off offset:128
	global_load_dword v249, v[82:83], off offset:192
	global_load_dword v250, v[82:83], off offset:256
	global_load_dword v251, v[82:83], off offset:320
	global_load_dword v252, v[82:83], off offset:384
	global_load_dword v253, v[82:83], off offset:448
	s_cmp_gt_i32 s54, 0
	s_cbranch_scc1 .Lscpf_l1_pre
	s_lshl_b64 s[100:101], s[98:99], 14
	v_lshl_add_u64 v[234:235], v[142:143], 0, s[100:101]
	global_load_dwordx4 v[222:225], v[234:235], off
	global_load_dwordx4 v[226:229], v[234:235], off offset:64
	global_load_dwordx4 v[230:233], v[234:235], off offset:128
	s_nop 0
	global_load_dwordx4 v[234:237], v[234:235], off offset:192
	s_lshl_b64 s[100:101], s[98:99], 13
	v_lshl_add_u64 v[242:243], v[144:145], 0, s[100:101]
	global_load_dwordx4 v[238:241], v[242:243], off
	s_nop 0
	global_load_dwordx4 v[242:245], v[242:243], off offset:64

.LBB0_1163:
	s_nop 3
	ds_read_b128 v[192:195], v183 offset:17408
	ds_read_b128 v[196:199], v183 offset:17472
	v_pk_mul_f32 v[4:5], v[4:5], v[184:185] op_sel_hi:[1,0]
	v_pk_mul_f32 v[2:3], v[2:3], v[184:185] op_sel_hi:[1,0]
	v_pk_mul_f32 v[8:9], v[8:9], v[182:183] op_sel_hi:[1,0]
	v_pk_mul_f32 v[6:7], v[6:7], v[182:183] op_sel_hi:[1,0]
	s_waitcnt lgkmcnt(1)
	v_mfma_f32_16x16x32_bf16 v[2:5], v[86:89], v[192:195], v[2:5]
	ds_read_b128 v[192:195], v125 offset:17408
	v_pk_mul_f32 v[20:21], v[20:21], v[180:181] op_sel_hi:[1,0]
	v_pk_mul_f32 v[18:19], v[18:19], v[180:181] op_sel_hi:[1,0]
	s_waitcnt lgkmcnt(1)
	v_mfma_f32_16x16x32_bf16 v[2:5], v[82:85], v[196:199], v[2:5]
	ds_read_b128 v[196:199], v125 offset:17472
	v_pk_mul_f32 v[12:13], v[12:13], v[178:179] op_sel_hi:[1,0]
	v_pk_mul_f32 v[10:11], v[10:11], v[178:179] op_sel_hi:[1,0]
	s_waitcnt lgkmcnt(1)
	v_mfma_f32_16x16x32_bf16 v[6:9], v[86:89], v[192:195], v[6:9]
	ds_read_b128 v[192:195], v185 offset:17408
	v_pk_mul_f32 v[24:25], v[24:25], v[176:177] op_sel_hi:[1,0]
	v_pk_mul_f32 v[22:23], v[22:23], v[176:177] op_sel_hi:[1,0]
	s_waitcnt lgkmcnt(1)
	v_mfma_f32_16x16x32_bf16 v[6:9], v[82:85], v[196:199], v[6:9]
	ds_read_b128 v[196:199], v185 offset:17472
	ds_read_b128 v[176:179], v127 offset:17472
	v_pk_mul_f32 v[16:17], v[16:17], v[174:175] op_sel_hi:[1,0]
	s_waitcnt lgkmcnt(2)
	v_mfma_f32_16x16x32_bf16 v[18:21], v[86:89], v[192:195], v[18:21]
	ds_read_b128 v[192:195], v186 offset:17408
	v_pk_mul_f32 v[14:15], v[14:15], v[174:175] op_sel_hi:[1,0]
	v_pk_mul_f32 v[28:29], v[28:29], v[172:173] op_sel_hi:[1,0]
	s_waitcnt lgkmcnt(2)
	v_mfma_f32_16x16x32_bf16 v[18:21], v[82:85], v[196:199], v[18:21]
	ds_read_b128 v[196:199], v186 offset:17472
	v_pk_mul_f32 v[26:27], v[26:27], v[172:173] op_sel_hi:[1,0]
	v_pk_mul_f32 v[32:33], v[32:33], v[170:171] op_sel_hi:[1,0]
	s_waitcnt lgkmcnt(1)
	v_mfma_f32_16x16x32_bf16 v[10:13], v[86:89], v[192:195], v[10:13]
	ds_read_b128 v[192:195], v127 offset:17408
	v_pk_mul_f32 v[30:31], v[30:31], v[170:171] op_sel_hi:[1,0]
	s_add_i32 s60, s60, -1
	s_waitcnt lgkmcnt(0)
	v_mfma_f32_16x16x32_bf16 v[22:25], v[86:89], v[192:195], v[22:25]
	ds_read_b128 v[192:195], v129 offset:17408
	s_cmp_eq_u32 s58, s56
	v_mfma_f32_16x16x32_bf16 v[22:25], v[82:85], v[176:179], v[22:25]
	ds_read_b128 v[174:177], v129 offset:17472
	s_waitcnt lgkmcnt(1)
	v_mfma_f32_16x16x32_bf16 v[14:17], v[86:89], v[192:195], v[14:17]
	ds_read_b128 v[192:195], v133 offset:17408
	s_waitcnt lgkmcnt(1)
	v_mfma_f32_16x16x32_bf16 v[14:17], v[82:85], v[174:177], v[14:17]
	ds_read_b128 v[172:175], v133 offset:17472
	ds_read_b128 v[176:179], v181 offset:17408
	s_waitcnt lgkmcnt(2)
	v_mfma_f32_16x16x32_bf16 v[26:29], v[86:89], v[192:195], v[26:29]
	s_waitcnt lgkmcnt(1)
	v_mfma_f32_16x16x32_bf16 v[26:29], v[82:85], v[172:175], v[26:29]
	ds_read_b128 v[170:173], v181 offset:17472
	s_waitcnt lgkmcnt(1)
	v_mfma_f32_16x16x32_bf16 v[30:33], v[86:89], v[176:179], v[30:33]
	v_mfma_f32_16x16x32_bf16 v[10:13], v[82:85], v[196:199], v[10:13]
	s_waitcnt lgkmcnt(0)
	v_mfma_f32_16x16x32_bf16 v[30:33], v[82:85], v[170:173], v[30:33]
	s_cbranch_scc1 .LBB0_1170
.LBB0_1164:
	s_cmp_ge_i32 s56, s54
	s_cselect_b64 s[30:31], -1, 0
	s_and_b64 s[6:7], s[24:25], exec
	s_cselect_b32 s6, s56, s60
	s_add_i32 s28, s6, s20
	s_ashr_i32 s29, s28, 31
	s_cmp_gt_i32 s56, s54
	s_cbranch_scc1 .Lscpf_l1_w4
	s_waitcnt vmcnt(0)
	s_branch .Lscpf_l1_wd

.Lscpf_l1_wd:
	v_mov_b32_e32 v184, v246
	v_mov_b32_e32 v182, v247
	v_mov_b32_e32 v180, v248
	v_mov_b32_e32 v178, v249
	v_mov_b32_e32 v176, v250
	v_mov_b32_e32 v174, v251
	v_mov_b32_e32 v172, v252
	v_mov_b32_e32 v170, v253
	s_cmp_lt_i32 s56, s54
	s_cbranch_scc1 .Lscpf_l1_nq
	v_mov_b32_e32 v38, v222
	v_mov_b32_e32 v39, v223
	v_mov_b32_e32 v40, v224
	v_mov_b32_e32 v41, v225
	v_mov_b32_e32 v34, v226
	v_mov_b32_e32 v35, v227
	v_mov_b32_e32 v36, v228
	v_mov_b32_e32 v37, v229
	v_mov_b32_e32 v42, v230
	v_mov_b32_e32 v43, v231
	v_mov_b32_e32 v44, v232
	v_mov_b32_e32 v45, v233
	v_mov_b32_e32 v46, v234
	v_mov_b32_e32 v47, v235
	v_mov_b32_e32 v48, v236
	v_mov_b32_e32 v49, v237
	v_mov_b32_e32 v54, v238
	v_mov_b32_e32 v55, v239
	v_mov_b32_e32 v56, v240
	v_mov_b32_e32 v57, v241
	v_mov_b32_e32 v50, v242
	v_mov_b32_e32 v51, v243
	v_mov_b32_e32 v52, v244
	v_mov_b32_e32 v53, v245
.Lscpf_l1_nq:
	s_barrier
	ds_write_b128 v187, v[66:69] offset:17408
	ds_write_b128 v187, v[70:73] offset:22016
	ds_write_b128 v187, v[74:77] offset:26624
	ds_write_b128 v187, v[78:81] offset:31232
	ds_write_b128 v187, v[62:65] offset:35840
	v_cndmask_b32_e64 v62, 0, 1, s[30:31]
	v_cmp_ne_u32_e64 s[6:7], 1, v62
	s_andn2_b64 vcc, exec, s[30:31]
	ds_write_b128 v187, v[58:61] offset:40448
	s_cbranch_vccnz .LBB0_1168
	v_cvt_pk_bf16_f32 v58, v2, s0
	ds_write_b16 v188, v58
	v_cvt_pk_bf16_f32 v58, v3, s0
	ds_write_b16 v188, v58 offset:272
	v_cvt_pk_bf16_f32 v58, v4, s0
	ds_write_b16 v188, v58 offset:544
	v_cvt_pk_bf16_f32 v58, v5, s0
	ds_write_b16 v188, v58 offset:816
	v_cvt_pk_bf16_f32 v58, v6, s0
	ds_write_b16 v188, v58 offset:32
	v_cvt_pk_bf16_f32 v58, v7, s0
	ds_write_b16 v188, v58 offset:304
	v_cvt_pk_bf16_f32 v58, v8, s0
	ds_write_b16 v188, v58 offset:576
	v_cvt_pk_bf16_f32 v58, v9, s0
	ds_write_b16 v188, v58 offset:848
	v_cvt_pk_bf16_f32 v58, v18, s0
	ds_write_b16 v188, v58 offset:64
	v_cvt_pk_bf16_f32 v58, v19, s0
	ds_write_b16 v188, v58 offset:336
	v_cvt_pk_bf16_f32 v58, v20, s0
	ds_write_b16 v188, v58 offset:608
	v_cvt_pk_bf16_f32 v58, v21, s0
	ds_write_b16 v188, v58 offset:880
	v_cvt_pk_bf16_f32 v58, v10, s0
	ds_write_b16 v188, v58 offset:96
	v_cvt_pk_bf16_f32 v58, v11, s0
	ds_write_b16 v188, v58 offset:368
	v_cvt_pk_bf16_f32 v58, v12, s0
	ds_write_b16 v188, v58 offset:640
	v_cvt_pk_bf16_f32 v58, v13, s0
	ds_write_b16 v188, v58 offset:912
	v_cvt_pk_bf16_f32 v58, v22, s0
	ds_write_b16 v188, v58 offset:128
	v_cvt_pk_bf16_f32 v58, v23, s0
	ds_write_b16 v188, v58 offset:400
	v_cvt_pk_bf16_f32 v58, v24, s0
	ds_write_b16 v188, v58 offset:672
	v_cvt_pk_bf16_f32 v58, v25, s0
	ds_write_b16 v188, v58 offset:944
	v_cvt_pk_bf16_f32 v58, v14, s0
	ds_write_b16 v188, v58 offset:160
	v_cvt_pk_bf16_f32 v58, v15, s0
	ds_write_b16 v188, v58 offset:432
	v_cvt_pk_bf16_f32 v58, v16, s0
	ds_write_b16 v188, v58 offset:704
	v_cvt_pk_bf16_f32 v58, v17, s0
	ds_write_b16 v188, v58 offset:976
	v_cvt_pk_bf16_f32 v58, v26, s0
	ds_write_b16 v188, v58 offset:192
	v_cvt_pk_bf16_f32 v58, v27, s0
	ds_write_b16 v188, v58 offset:464
	v_cvt_pk_bf16_f32 v58, v28, s0
	ds_write_b16 v188, v58 offset:736
	v_cvt_pk_bf16_f32 v58, v29, s0
	ds_write_b16 v188, v58 offset:1008
	v_cvt_pk_bf16_f32 v58, v30, s0
	ds_write_b16 v188, v58 offset:224
	v_cvt_pk_bf16_f32 v58, v31, s0
	ds_write_b16 v188, v58 offset:496
	v_cvt_pk_bf16_f32 v58, v32, s0
	ds_write_b16 v188, v58 offset:768
	v_cvt_pk_bf16_f32 v58, v33, s0
	ds_write_b16 v188, v58 offset:1040
.LBB0_1168:
	s_add_i32 s56, s56, 1
	s_min_i32 s29, s56, s57
	s_sub_i32 s61, s55, s29
	s_and_b64 s[30:31], s[24:25], exec
	s_cselect_b32 s29, s29, s61
	s_add_i32 s30, s29, s20
	s_ashr_i32 s31, s30, 31
	s_lshl_b64 s[98:99], s[30:31], 3
	s_or_b64 s[98:99], s[98:99], s[26:27]
	s_lshl_b32 s29, s26, 14
	s_lshl_b64 s[30:31], s[30:31], 17
	s_or_b32 s62, s30, s29
	s_mov_b32 s63, s31
	v_lshl_add_u64 v[58:59], v[148:149], 0, s[62:63]
	v_add_co_u32_e32 v60, vcc, s33, v58
	s_waitcnt lgkmcnt(0)
	s_nop 0
	v_addc_co_u32_e32 v61, vcc, 0, v59, vcc
	s_barrier
	global_load_dwordx4 v[66:69], v[58:59], off
	global_load_dwordx4 v[70:73], v[60:61], off
	v_add_co_u32_e32 v60, vcc, 0x2000, v58
	s_or_b32 s30, s30, s59
	s_nop 0
	v_addc_co_u32_e32 v61, vcc, 0, v59, vcc
	v_add_co_u32_e32 v58, vcc, 0x3000, v58
	s_nop 1
	v_addc_co_u32_e32 v59, vcc, 0, v59, vcc
	global_load_dwordx4 v[74:77], v[60:61], off
	global_load_dwordx4 v[78:81], v[58:59], off
	v_lshl_add_u64 v[58:59], v[150:151], 0, s[30:31]
	v_add_co_u32_e32 v60, vcc, 0x1000, v58
	s_nop 1
	v_addc_co_u32_e32 v61, vcc, 0, v59, vcc
	global_load_dwordx4 v[62:65], v[58:59], off
	s_nop 0
	global_load_dwordx4 v[58:61], v[60:61], off
	s_cmp_gt_i32 s56, s57
	s_cbranch_scc1 .Lscpf_l1_nopf
	s_lshl_b64 s[100:101], s[98:99], 9
	v_lshl_add_u64 v[82:83], v[146:147], 0, s[100:101]
	global_load_dword v246, v[82:83], off
	global_load_dword v247, v[82:83], off offset:64
	global_load_dword v248, v[82:83], off offset:128
	global_load_dword v249, v[82:83], off offset:192
	global_load_dword v250, v[82:83], off offset:256
	global_load_dword v251, v[82:83], off offset:320
	global_load_dword v252, v[82:83], off offset:384
	global_load_dword v253, v[82:83], off offset:448
	s_cmp_lt_i32 s56, s54
	s_cbranch_scc1 .Lscpf_l1_nopf
	s_lshl_b64 s[100:101], s[98:99], 14
	v_lshl_add_u64 v[234:235], v[142:143], 0, s[100:101]
	global_load_dwordx4 v[222:225], v[234:235], off
	global_load_dwordx4 v[226:229], v[234:235], off offset:64
	global_load_dwordx4 v[230:233], v[234:235], off offset:128
	s_nop 0
	global_load_dwordx4 v[234:237], v[234:235], off offset:192
	s_lshl_b64 s[100:101], s[98:99], 13
	v_lshl_add_u64 v[242:243], v[144:145], 0, s[100:101]
	global_load_dwordx4 v[238:241], v[242:243], off
	s_nop 0
	global_load_dwordx4 v[242:245], v[242:243], off offset:64
.Lscpf_l1_nopf:
	ds_read_b128 v[86:89], v123 offset:35840
	ds_read_b128 v[82:85], v123 offset:35904
	s_and_b64 vcc, exec, s[6:7]
	s_cbranch_vccnz .LBB0_1163
	v_add_u32_e32 v91, v121, v117
	ds_read_b128 v[192:195], v190 offset:35840
	ds_read_b128 v[196:199], v91 offset:35840
	ds_read_b128 v[200:203], v190 offset:35904
	ds_read_b128 v[204:207], v91 offset:35904
	ds_read_b128 v[208:211], v189
	s_waitcnt lgkmcnt(3)
	v_mfma_f32_16x16x32_bf16 v[196:199], v[196:199], v[54:57], 0
	v_lshl_add_u32 v216, s28, 6, v119
	v_ashrrev_i32_e32 v217, 31, v216
	v_lshlrev_b64 v[220:221], 11, v[216:217]
	s_waitcnt lgkmcnt(1)
	v_mfma_f32_16x16x32_bf16 v[196:199], v[204:207], v[50:53], v[196:199]
	ds_read_b128 v[204:207], v189 offset:64
	v_lshl_add_u64 v[220:221], v[168:169], 0, v[220:221]
	ds_read_b128 v[216:219], v189 offset:13120
	s_waitcnt lgkmcnt(2)
	v_mfma_f32_16x16x32_bf16 v[196:199], v[208:211], v[38:41], v[196:199]
	ds_read_b128 v[208:211], v189 offset:128
	ds_read_b128 v[212:215], v189 offset:13056
	s_waitcnt lgkmcnt(3)
	v_mfma_f32_16x16x32_bf16 v[196:199], v[204:207], v[34:37], v[196:199]
	ds_read_b128 v[204:207], v189 offset:192
	v_mfma_f32_16x16x32_bf16 v[192:195], v[192:195], v[54:57], 0
	s_waitcnt lgkmcnt(2)
	v_mfma_f32_16x16x32_bf16 v[196:199], v[208:211], v[42:45], v[196:199]
	ds_read_b128 v[208:211], v189 offset:8704
	v_mfma_f32_16x16x32_bf16 v[192:195], v[200:203], v[50:53], v[192:195]
	ds_read_b128 v[200:203], v189 offset:4416
	s_waitcnt lgkmcnt(2)
	v_mfma_f32_16x16x32_bf16 v[196:199], v[204:207], v[46:49], v[196:199]
	ds_read_b128 v[204:207], v189 offset:4352
	s_waitcnt lgkmcnt(0)
	v_mfma_f32_16x16x32_bf16 v[192:195], v[204:207], v[38:41], v[192:195]
	ds_read_b128 v[204:207], v189 offset:4480
	s_nop 3
	v_cvt_pk_bf16_f32 v196, v196, v197
	v_cvt_pk_bf16_f32 v197, v198, v199
	v_mfma_f32_16x16x32_bf16 v[192:195], v[200:203], v[34:37], v[192:195]
	ds_read_b128 v[200:203], v189 offset:4544
	global_store_dwordx2 v[220:221], v[196:197], off
	ds_read_b128 v[196:199], v189 offset:13248
	s_waitcnt lgkmcnt(2)
	v_mfma_f32_16x16x32_bf16 v[192:195], v[204:207], v[42:45], v[192:195]
	ds_read_b128 v[204:207], v190 offset:38144
	s_waitcnt lgkmcnt(2)
	v_mfma_f32_16x16x32_bf16 v[192:195], v[200:203], v[46:49], v[192:195]
	ds_read_b128 v[200:203], v190 offset:38208
	s_waitcnt lgkmcnt(1)
	v_mfma_f32_16x16x32_bf16 v[204:207], v[204:207], v[54:57], 0
	s_nop 4
	v_cvt_pk_bf16_f32 v192, v192, v193
	s_waitcnt lgkmcnt(0)
	v_mfma_f32_16x16x32_bf16 v[200:203], v[200:203], v[50:53], v[204:207]
	v_cvt_pk_bf16_f32 v193, v194, v195
	global_store_dwordx2 v[220:221], v[192:193], off offset:32
	s_nop 0
	ds_read_b128 v[204:207], v189 offset:8768
	v_mfma_f32_16x16x32_bf16 v[200:203], v[208:211], v[38:41], v[200:203]
	ds_read_b128 v[208:211], v189 offset:8832
	s_waitcnt lgkmcnt(1)
	v_mfma_f32_16x16x32_bf16 v[200:203], v[204:207], v[34:37], v[200:203]
	ds_read_b128 v[204:207], v189 offset:8896
	s_waitcnt lgkmcnt(1)
	v_mfma_f32_16x16x32_bf16 v[200:203], v[208:211], v[42:45], v[200:203]
	ds_read_b128 v[208:211], v190 offset:40448
	s_waitcnt lgkmcnt(1)
	v_mfma_f32_16x16x32_bf16 v[200:203], v[204:207], v[46:49], v[200:203]
	ds_read_b128 v[204:207], v190 offset:40512
	s_waitcnt lgkmcnt(1)
	v_mfma_f32_16x16x32_bf16 v[208:211], v[208:211], v[54:57], 0
	s_nop 4
	v_cvt_pk_bf16_f32 v200, v200, v201
	v_cvt_pk_bf16_f32 v201, v202, v203
	global_store_dwordx2 v[220:221], v[200:201], off offset:64
	s_waitcnt lgkmcnt(0)
	v_mfma_f32_16x16x32_bf16 v[204:207], v[204:207], v[50:53], v[208:211]
	s_nop 2
	ds_read_b128 v[208:211], v189 offset:13184
	v_mfma_f32_16x16x32_bf16 v[204:207], v[212:215], v[38:41], v[204:207]
	v_mfma_f32_16x16x32_bf16 v[204:207], v[216:219], v[34:37], v[204:207]
	s_waitcnt lgkmcnt(0)
	v_mfma_f32_16x16x32_bf16 v[192:195], v[208:211], v[42:45], v[204:207]
	v_mfma_f32_16x16x32_bf16 v[192:195], v[196:199], v[46:49], v[192:195]
	s_nop 7
	v_cvt_pk_bf16_f32 v192, v192, v193
	v_cvt_pk_bf16_f32 v193, v194, v195
	global_store_dwordx2 v[220:221], v[192:193], off offset:96
	s_branch .LBB0_1163
